# attention loop: K/V tiles staged by direct global-to-LDS DMA in LDS-image order (no register staging, no ds_write), persistent -m_ref accumulator-init block
# speedup vs baseline: 1.0527x; 1.0394x over previous
; __device__ __forceinline__ int v_st(int k, int c) { const int kk = (k & ~0xC) | ((k & 4) << 1) | ((k & 8) >> 1); return ((kk >> 3) * 4 + (c >> 5)) * 512 + ((kk & 7) * 32 + (c & 31)) * 2; }
; __device__ __forceinline__ int v_rd_base(int lane) { return ((lane & 3) << 3) | (((lane >> 2) & 3) << 6) | (((lane >> 4) & 1) << 5) | (((lane >> 5) & 1) << 8); }
; #define SLOAD(i, k0) do { sr_[i].vs0 = *reinterpret_cast<const bf16x8*>(&Vh[(long)((k0) + sr) * LDQ + sc]); sr_[i].vs1 = *reinterpret_cast<const bf16x8*>(&Vh[(long)((k0) + 32 + sr) * LDQ + sc]); \
;     sr_[i].ks0 = *reinterpret_cast<const bf16x8*>(&Kh[(long)((k0) + kr) * LDQ + kc]); } while (0)
; #define SWRITE(b, i) do { *(bf16x8*)(V_lds + (b) * SHM_V + vst0) = sr_[i].vs0; *(bf16x8*)(V_lds + (b) * SHM_V + vst1) = sr_[i].vs1; \
;     *(bf16x8*)(K_lds + (b) * SHM_K + kst) = sr_[i].ks0; } while (0)
; __device__ __forceinline__ void attn_unit(const bf16_t* __restrict__ Qb, const bf16_t* __restrict__ Kh, const bf16_t* __restrict__ Vh, int seq, char* lds,
;                                           int mode, float* scratch, float lam, float gscale, const float* __restrict__ subg, bf16_t* outp) {
;     ...
;   const int tid = tid_, wid = tid >> 6, lane = tid & 63, r32 = lane & 31, hi = lane >> 5;
;   char* V_lds = lds; char* K_lds = lds + 3 * SHM_V;
;   float* ws = (float*)(lds + 3 * SHM_V + 3 * SHM_K) + wid * 64; float* li_l = ws; float* al_l = ws + 32;
;   float m_reg = 0.f, l_reg = 0; f32x16 o[4] = {}; bf16x8 qr[4];
;   const bf16_t* Qw = Qb + (long)(wid * QBLK + r32) * LDQ + hi * 8;
; #pragma unroll
;   for (int d0 = 0; d0 < 4; ++d0) qr[d0] = *reinterpret_cast<const bf16x8*>(Qw + d0 * 16);
;   const int sr = tid >> 4, sc = (tid & 15) * 8, vst0 = v_st(sr, sc), vst1 = v_st(32 + sr, sc);
;   const int kr = tid >> 3, kc = (tid & 7) * 8, kst = KSWZ(kr, kc * 2);
;   const int vb0 = (int)(uintptr_t)V_lds + v_rd_base(lane);
;   struct { bf16x8 vs0, vs1, ks0; } sr_[2];
;     ...
;   f32x16 pA0, pA1, pB0, pB1; float alA, alB; bf16x8 pa0, pa1, pa2, pa3; const int NT = seq / KVBLK;
;   constexpr int SE = 0, SO = 1;
;   SLOAD(SE, 0); asm volatile("s_waitcnt vmcnt(0)" ::: "memory"); SWRITE(0, SE); __syncthreads();
;   qkt(pA0, pA1, K_lds, qr, r32, hi, m_reg); partialSM(pA0, pA1, m_reg, alA, true);
;   SLOAD(SO, KVBLK); if (2 < NT) SLOAD(SE, 2 * KVBLK);
;   SWAIT(); SWRITE(1, SO); __syncthreads();
.LBB0_1329:
	v_mov_b32_e32 v56, v214
	s_or_b32 s52, s24, s76
	v_ashrrev_i32_e32 v57, 6, v56
	v_and_b32_e32 v165, 31, v56
	v_lshlrev_b32_e32 v152, 5, v57
	s_lshl_b64 s[0:1], s[52:53], 1
	v_or_b32_e32 v0, v152, v165
	s_add_u32 s58, s74, s0
	v_ashrrev_i32_e32 v1, 31, v0
	s_addc_u32 s59, s75, s1
	v_bfe_u32 v164, v56, 5, 1
	v_lshlrev_b64 v[0:1], 10, v[0:1]
	v_lshl_add_u64 v[0:1], s[58:59], 0, v[0:1]
	v_lshlrev_b32_e32 v178, 4, v164
	v_lshl_add_u64 v[0:1], v[0:1], 0, v[178:179]
	global_load_dwordx4 v[124:127], v[0:1], off
	global_load_dwordx4 v[120:123], v[0:1], off offset:32
	global_load_dwordx4 v[116:119], v[0:1], off offset:64
	global_load_dwordx4 v[112:115], v[0:1], off offset:96
	v_ashrrev_i32_e32 v0, 4, v56
	v_and_b32_e32 v1, 0xfffff0, v0
	v_lshlrev_b32_e32 v3, 1, v0
	v_lshlrev_b32_e32 v12, 3, v56
	v_and_or_b32 v1, v3, 8, v1
	v_lshrrev_b32_e32 v3, 1, v0
	v_lshrrev_b32_e32 v1, 1, v1
	v_bfe_u32 v5, v12, 5, 2
	v_and_b32_e32 v4, 3, v0
	v_or_b32_e32 v1, v1, v5
	v_and_or_b32 v3, v3, 4, v4
	v_lshlrev_b32_e32 v6, 4, v56
	v_lshlrev_b32_e32 v1, 9, v1
	v_lshlrev_b32_e32 v3, 6, v3
	v_and_b32_e32 v7, 48, v6
	v_add_u32_e32 v4, 32, v0
	v_or3_b32 v168, v1, v3, v7
	v_and_b32_e32 v1, 0xfffff0, v4
	v_lshlrev_b32_e32 v8, 1, v4
	v_and_or_b32 v1, v8, 8, v1
	v_lshrrev_b32_e32 v1, 1, v1
	v_or_b32_e32 v1, v1, v5
	v_lshlrev_b32_e32 v1, 9, v1
	v_ashrrev_i32_e32 v8, 3, v56
	v_or3_b32 v169, v1, v3, v7
	v_lshrrev_b32_e32 v232, 7, v56
	v_lshlrev_b32_e32 v232, 11, v232
	v_bfe_u32 v233, v56, 2, 2
	v_lshl_or_b32 v232, v233, 9, v232
	v_bfe_u32 v233, v56, 4, 3
	v_lshl_or_b32 v232, v233, 6, v232
	v_and_b32_e32 v233, 3, v56
	v_lshl_or_b32 v168, v233, 4, v232
	v_add_u32_e32 v169, 0x2000, v168
	v_lshlrev_b32_e32 v1, 7, v8
	v_and_b32_e32 v10, 0x70, v6
	v_and_b32_e32 v3, 0x70, v56
	v_bitop3_b32 v170, v10, v1, v3 bitop3:0xde
	v_ashrrev_i32_e32 v1, 31, v0
	v_ashrrev_i32_e32 v5, 31, v4
	s_add_u32 s20, s77, s0
	v_and_b32_e32 v2, 0x78, v12
	v_lshlrev_b64 v[48:49], 10, v[0:1]
	v_lshlrev_b64 v[4:5], 10, v[4:5]
	v_ashrrev_i32_e32 v9, 31, v8
	s_addc_u32 s21, s78, s1
	v_lshl_add_u64 v[0:1], s[18:19], 0, v[48:49]
	v_lshlrev_b32_e32 v6, 1, v2
	v_mov_b32_e32 v7, v179
	v_lshl_add_u64 v[4:5], s[18:19], 0, v[4:5]
	v_lshlrev_b64 v[50:51], 10, v[8:9]
	v_lshl_add_u64 v[52:53], v[0:1], 0, v[6:7]
	v_lshl_add_u64 v[4:5], v[4:5], 0, v[6:7]
	v_lshl_add_u64 v[8:9], s[20:21], 0, v[50:51]
	v_mov_b32_e32 v11, v179
	global_load_dwordx4 v[0:3], v[52:53], off
	v_lshl_add_u64 v[54:55], v[8:9], 0, v[10:11]
	global_load_dwordx4 v[4:7], v[4:5], off
	v_lshlrev_b32_e32 v64, 7, v165
	global_load_dwordx4 v[8:11], v[54:55], off
	v_and_b32_e32 v65, 0x70, v12
	v_add_u32_e32 v58, 0, v168
	v_add_u32_e32 v59, 0, v169
	v_bitop3_b32 v173, v178, v64, v65 bitop3:0xde
	s_waitcnt vmcnt(0)
	v_add_u32_e32 v171, 0, v170
	v_mov_b64_e32 v[32:33], s[36:37]
	v_mov_b64_e32 v[34:35], s[38:39]
	v_mov_b64_e32 v[36:37], s[40:41]
	v_mov_b64_e32 v[38:39], s[42:43]
	v_mov_b64_e32 v[40:41], s[44:45]
	v_mov_b64_e32 v[42:43], s[46:47]
	v_mov_b64_e32 v[44:45], s[48:49]
	v_mov_b64_e32 v[46:47], s[50:51]
	s_mov_b32 s0, 0x18000
	s_waitcnt vmcnt(2)
	ds_write_b128 v58, v[0:3]
	s_waitcnt vmcnt(1)
	ds_write_b128 v59, v[4:7]
	v_add_u32_e32 v4, 0, v173
	s_waitcnt vmcnt(0)
	ds_write_b128 v171, v[8:11] offset:49152
	s_waitcnt lgkmcnt(0)
	s_barrier
	ds_read_b128 v[0:3], v4 offset:49152
	ds_read_b128 v[60:63], v4 offset:53248
	s_waitcnt lgkmcnt(1)
	v_mfma_f32_32x32x16_bf16 v[16:31], v[0:3], v[124:127], v[32:47]
	s_waitcnt lgkmcnt(0)
	v_mfma_f32_32x32x16_bf16 v[0:15], v[60:63], v[124:127], v[32:47]
	s_nop 6
	v_or_b32_e32 v32, 32, v178
	v_bitop3_b32 v175, v32, v64, v65 bitop3:0xde
	v_add_u32_e32 v36, 0, v175
	ds_read_b128 v[32:35], v36 offset:49152
	ds_read_b128 v[36:39], v36 offset:53248
	s_waitcnt lgkmcnt(1)
	v_mfma_f32_32x32x16_bf16 v[16:31], v[32:35], v[120:123], v[16:31]
	v_or_b32_e32 v32, 64, v178
	v_bitop3_b32 v174, v32, v64, v65 bitop3:0xde
	s_waitcnt lgkmcnt(0)
	v_mfma_f32_32x32x16_bf16 v[0:15], v[36:39], v[120:123], v[0:15]
	v_add_u32_e32 v36, 0, v174
	ds_read_b128 v[32:35], v36 offset:49152
	ds_read_b128 v[36:39], v36 offset:53248
	s_waitcnt lgkmcnt(1)
	v_mfma_f32_32x32x16_bf16 v[16:31], v[32:35], v[116:119], v[16:31]
	v_or_b32_e32 v32, 0x60, v178
	v_bitop3_b32 v176, v32, v64, v65 bitop3:0xde
	s_waitcnt lgkmcnt(0)
	v_mfma_f32_32x32x16_bf16 v[0:15], v[36:39], v[116:119], v[0:15]
	v_add_u32_e32 v36, 0, v176
	ds_read_b128 v[32:35], v36 offset:49152
	ds_read_b128 v[36:39], v36 offset:53248
	s_waitcnt lgkmcnt(1)
	v_mfma_f32_32x32x16_bf16 v[16:31], v[32:35], v[112:115], v[16:31]
	s_waitcnt lgkmcnt(0)
	v_mfma_f32_32x32x16_bf16 v[0:15], v[36:39], v[112:115], v[0:15]
	s_nop 9
	v_max_f32_e32 v32, v17, v17
	v_max_f32_e32 v33, v16, v16
	v_max_f32_e32 v32, v33, v32
	v_max3_f32 v32, v32, v18, v19
	v_max3_f32 v32, v32, v20, v21
	v_max3_f32 v32, v32, v22, v23
	v_max3_f32 v32, v32, v24, v25
	v_max3_f32 v32, v32, v26, v27
	v_max3_f32 v32, v32, v28, v29
	v_max3_f32 v32, v32, v30, v31
	v_max3_f32 v32, v32, v0, v1
	v_max3_f32 v32, v32, v2, v3
	v_max3_f32 v32, v32, v4, v5
	v_max3_f32 v32, v32, v6, v7
	v_max3_f32 v32, v32, v8, v9
	v_max3_f32 v32, v32, v10, v11
	v_max3_f32 v32, v32, v12, v13
	v_max3_f32 v36, v32, v14, v15
	v_add_co_u32_e32 v32, vcc, s63, v52
	v_mov_b32_e32 v37, v36
	s_nop 0
	v_addc_co_u32_e32 v33, vcc, 0, v53, vcc
	v_add_co_u32_e32 v38, vcc, s0, v52
	s_mov_b32 s0, 0x20000
	s_nop 0
	v_addc_co_u32_e32 v39, vcc, 0, v53, vcc
	v_add_co_u32_e32 v42, vcc, s63, v54
	global_load_dwordx4 v[32:35], v[32:33], off
	s_nop 0
	v_addc_co_u32_e32 v43, vcc, 0, v55, vcc
	v_add_co_u32_e32 v46, vcc, s0, v52
	global_load_dwordx4 v[42:45], v[42:43], off
	s_nop 0
	v_addc_co_u32_e32 v47, vcc, 0, v53, vcc
	global_load_dwordx4 v[128:131], v[46:47], off
	v_add_co_u32_e32 v46, vcc, 0x28000, v52
	global_load_dwordx4 v[38:41], v[38:39], off
	s_nop 0
	v_addc_co_u32_e32 v47, vcc, 0, v53, vcc
	global_load_dwordx4 v[132:135], v[46:47], off
	v_add_co_u32_e32 v46, vcc, 0x20000, v54
	v_permlane32_swap_b32_e32 v36, v37
	s_nop 0
	v_addc_co_u32_e32 v47, vcc, 0, v55, vcc
	global_load_dwordx4 v[136:139], v[46:47], off
	s_waitcnt vmcnt(3)
	v_cmp_lt_i32_e32 vcc, 3, v57
	s_waitcnt vmcnt(5)
	ds_write_b128 v58, v[32:35] offset:16384
	s_waitcnt vmcnt(2)
	ds_write_b128 v59, v[38:41] offset:16384
	ds_write_b128 v171, v[42:45] offset:57344
	s_waitcnt lgkmcnt(0)
	s_barrier
; __device__ __forceinline__ int v_st(int k, int c) { const int kk = (k & ~0xC) | ((k & 4) << 1) | ((k & 8) >> 1); return ((kk >> 3) * 4 + (c >> 5)) * 512 + ((kk & 7) * 32 + (c & 31)) * 2; }
; __device__ __forceinline__ int v_rd_base(int lane) { return ((lane & 3) << 3) | (((lane >> 2) & 3) << 6) | (((lane >> 4) & 1) << 5) | (((lane >> 5) & 1) << 8); }
; #define SLOAD(i, k0) do { sr_[i].vs0 = *reinterpret_cast<const bf16x8*>(&Vh[(long)((k0) + sr) * LDQ + sc]); sr_[i].vs1 = *reinterpret_cast<const bf16x8*>(&Vh[(long)((k0) + 32 + sr) * LDQ + sc]); \
;     sr_[i].ks0 = *reinterpret_cast<const bf16x8*>(&Kh[(long)((k0) + kr) * LDQ + kc]); } while (0)
; #define SWRITE(b, i) do { *(bf16x8*)(V_lds + (b) * SHM_V + vst0) = sr_[i].vs0; *(bf16x8*)(V_lds + (b) * SHM_V + vst1) = sr_[i].vs1; \
;     *(bf16x8*)(K_lds + (b) * SHM_K + kst) = sr_[i].ks0; } while (0)
; #define SWAIT() asm volatile("s_waitcnt vmcnt(3)" ::: "memory")
; __device__ __forceinline__ void attn_unit(const bf16_t* __restrict__ Qb, const bf16_t* __restrict__ Kh, const bf16_t* __restrict__ Vh, int seq, char* lds,
;                                           int mode, float* scratch, float lam, float gscale, const float* __restrict__ subg, bf16_t* outp) {
;     ...
;   const int sr = tid >> 4, sc = (tid & 15) * 8, vst0 = v_st(sr, sc), vst1 = v_st(32 + sr, sc);
;   const int kr = tid >> 3, kc = (tid & 7) * 8, kst = KSWZ(kr, kc * 2);
;   const int vb0 = (int)(uintptr_t)V_lds + v_rd_base(lane);
;   struct { bf16x8 vs0, vs1, ks0; } sr_[2];
;     ...
;   f32x16 pA0, pA1, pB0, pB1; float alA, alB; bf16x8 pa0, pa1, pa2, pa3; const int NT = seq / KVBLK;
;   constexpr int SE = 0, SO = 1;
;   SLOAD(SE, 0); asm volatile("s_waitcnt vmcnt(0)" ::: "memory"); SWRITE(0, SE); __syncthreads();
;   qkt(pA0, pA1, K_lds, qr, r32, hi, m_reg); partialSM(pA0, pA1, m_reg, alA, true);
;   SLOAD(SO, KVBLK); if (2 < NT) SLOAD(SE, 2 * KVBLK);
;   SWAIT(); SWRITE(1, SO); __syncthreads();
;   int bp = 0, bc = 1, bn = 2;
;     ...
;   if (wid >= 4) __builtin_amdgcn_s_setprio(1);
	s_and_saveexec_b64 s[20:21], vcc
	s_setprio 1
	s_or_b64 exec, exec, s[20:21]
	v_max_f32_e32 v33, v37, v37
	v_max_f32_e32 v34, v36, v36
	v_max_f32_e32 v33, v34, v33
	s_xor_b64 s[72:73], s[4:5], -1
	s_add_i32 s1, 0, 0x14000
	v_sub_f32_e32 v64, v0, v33
	v_and_b32_e32 v0, 15, v56
	v_and_b32_e32 v32, 63, v56
	v_sub_f32_e32 v16, v16, v33
	v_sub_f32_e32 v17, v17, v33
	s_cmp_lg_u32 0, -1
	v_sub_f32_e32 v65, v1, v33
	v_lshlrev_b32_e32 v0, 4, v0
	v_mov_b32_e32 v1, v179
	v_sub_f32_e32 v18, v18, v33
	v_exp_f32_e32 v160, v16
	v_exp_f32_e32 v192, v17
	v_and_b32_e32 v16, 0x3fffffc0, v56
	v_lshlrev_b32_e32 v17, 4, v32
	s_cselect_b32 s4, 0, 0
	v_lshl_add_u64 v[0:1], v[48:49], 0, v[0:1]
	s_add_i32 s52, s71, s24
	v_sub_f32_e32 v19, v19, v33
	v_sub_f32_e32 v20, v20, v33
	v_sub_f32_e32 v21, v21, v33
	v_sub_f32_e32 v22, v22, v33
	v_sub_f32_e32 v23, v23, v33
	v_sub_f32_e32 v24, v24, v33
	v_sub_f32_e32 v25, v25, v33
	v_sub_f32_e32 v26, v26, v33
	v_sub_f32_e32 v27, v27, v33
	v_sub_f32_e32 v28, v28, v33
	v_sub_f32_e32 v29, v29, v33
	v_sub_f32_e32 v30, v30, v33
	v_sub_f32_e32 v31, v31, v33
	v_exp_f32_e32 v151, v18
	v_lshl_add_u32 v166, v16, 2, s1
	v_lshlrev_b32_e32 v16, 3, v32
	v_and_b32_e32 v17, 0xc0, v17
	v_lshlrev_b32_e32 v18, 1, v32
	v_lshl_add_u64 v[154:155], s[28:29], 0, v[0:1]
	v_and_b32_e32 v0, 7, v56
	s_lshl_b64 s[20:21], s[52:53], 1
	v_exp_f32_e32 v161, v19
	v_exp_f32_e32 v149, v20
	v_exp_f32_e32 v159, v21
	v_exp_f32_e32 v148, v22
	v_exp_f32_e32 v150, v23
	v_exp_f32_e32 v145, v24
	v_exp_f32_e32 v147, v25
	v_exp_f32_e32 v143, v26
	v_exp_f32_e32 v146, v27
	v_exp_f32_e32 v141, v28
	v_exp_f32_e32 v144, v29
	v_exp_f32_e32 v140, v30
	v_exp_f32_e32 v142, v31
	v_and_or_b32 v17, v16, 24, v17
	v_and_b32_e32 v18, 32, v18
	v_and_b32_e32 v16, 0x100, v16
	v_lshlrev_b32_e32 v0, 4, v0
	v_mov_b32_e32 v1, v179
	s_add_u32 s20, s10, s20
	v_or3_b32 v16, v17, v18, v16
	v_sub_f32_e32 v79, v15, v33
	v_sub_f32_e32 v78, v14, v33
	v_lshl_add_u64 v[0:1], v[50:51], 0, v[0:1]
	s_addc_u32 s21, s11, s21
	v_mov_b32_e32 v14, v179
	v_mov_b32_e32 v15, v179
	v_add_u32_e32 v177, s4, v16
	v_add_f32_e32 v181, 0, v33
	v_sub_f32_e32 v77, v13, v33
	v_sub_f32_e32 v76, v12, v33
	v_sub_f32_e32 v75, v11, v33
	v_sub_f32_e32 v74, v10, v33
	v_sub_f32_e32 v73, v9, v33
	v_sub_f32_e32 v72, v8, v33
	v_sub_f32_e32 v71, v7, v33
	v_sub_f32_e32 v70, v6, v33
	v_sub_f32_e32 v69, v5, v33
	v_sub_f32_e32 v68, v4, v33
	v_sub_f32_e32 v67, v3, v33
	v_sub_f32_e32 v66, v2, v33
	v_cmp_gt_u32_e64 s[4:5], 32, v32
	v_lshl_add_u64 v[156:157], s[20:21], 0, v[0:1]
	v_mov_b32_e32 v0, v179
	v_mov_b32_e32 v1, v179
	v_mov_b32_e32 v2, v179
	v_mov_b32_e32 v3, v179
	v_mov_b32_e32 v4, v179
	v_mov_b32_e32 v5, v179
	v_mov_b32_e32 v6, v179
	v_mov_b32_e32 v7, v179
	v_mov_b32_e32 v8, v179
	v_mov_b32_e32 v9, v179
	v_mov_b32_e32 v10, v179
	v_mov_b32_e32 v11, v179
	v_mov_b32_e32 v12, v179
	v_mov_b32_e32 v13, v179
	v_mov_b64_e32 v[62:63], v[14:15]
	v_mov_b64_e32 v[46:47], v[14:15]
	v_mov_b64_e32 v[30:31], v[14:15]
	s_mov_b32 s0, 2
	s_mov_b32 s1, 1
	s_mov_b32 s2, 0
	v_lshl_add_u32 v153, v165, 2, v166
	v_mov_b32_e32 v167, 0
	v_mov_b32_e32 v186, 1.0
	v_mov_b64_e32 v[60:61], v[12:13]
	v_mov_b64_e32 v[58:59], v[10:11]
	v_mov_b64_e32 v[56:57], v[8:9]
	v_mov_b64_e32 v[54:55], v[6:7]
	v_mov_b64_e32 v[52:53], v[4:5]
	v_mov_b64_e32 v[50:51], v[2:3]
	v_mov_b64_e32 v[48:49], v[0:1]
	v_mov_b64_e32 v[44:45], v[12:13]
	v_mov_b64_e32 v[42:43], v[10:11]
	v_mov_b64_e32 v[40:41], v[8:9]
	v_mov_b64_e32 v[38:39], v[6:7]
	v_mov_b64_e32 v[36:37], v[4:5]
	v_mov_b64_e32 v[34:35], v[2:3]
	v_mov_b64_e32 v[32:33], v[0:1]
	v_mov_b64_e32 v[28:29], v[12:13]
	v_mov_b64_e32 v[26:27], v[10:11]
	v_mov_b64_e32 v[24:25], v[8:9]
	v_mov_b64_e32 v[22:23], v[6:7]
	v_mov_b64_e32 v[20:21], v[4:5]
	v_mov_b64_e32 v[18:19], v[2:3]
	v_mov_b64_e32 v[16:17], v[0:1]
	s_mov_b32 s52, 1
	v_exp_f32_e32 v80, v64
	v_exp_f32_e32 v81, v65
	v_exp_f32_e32 v82, v66
	v_exp_f32_e32 v83, v67
	v_exp_f32_e32 v84, v68
	v_exp_f32_e32 v85, v69
	v_exp_f32_e32 v86, v70
	v_exp_f32_e32 v87, v71
	v_exp_f32_e32 v88, v72
	v_exp_f32_e32 v89, v73
	v_exp_f32_e32 v90, v74
	v_exp_f32_e32 v91, v75
	v_exp_f32_e32 v92, v76
	v_exp_f32_e32 v93, v77
	v_exp_f32_e32 v94, v78
	v_exp_f32_e32 v95, v79
	v_mov_b32_e32 v64, v160
	v_mov_b32_e32 v65, v192
	v_mov_b32_e32 v66, v151
	v_mov_b32_e32 v67, v161
	v_mov_b32_e32 v68, v149
	v_mov_b32_e32 v69, v159
	v_mov_b32_e32 v70, v148
	v_mov_b32_e32 v71, v150
	v_mov_b32_e32 v72, v145
	v_mov_b32_e32 v73, v147
	v_mov_b32_e32 v74, v143
	v_mov_b32_e32 v75, v146
	v_mov_b32_e32 v76, v141
	v_mov_b32_e32 v77, v144
	v_mov_b32_e32 v78, v140
	v_mov_b32_e32 v79, v142
	v_mov_b32_e32 v235, v186
	v_readfirstlane_b32 s24, v156
	v_readfirstlane_b32 s25, v157
	v_readfirstlane_b32 s79, v214
	v_readfirstlane_b32 s58, v154
	s_nop 3
	s_lshr_b32 s79, s79, 6
	s_lshl_b32 s20, s79, 13
	s_sub_u32 s24, s24, s20
	s_subb_u32 s25, s25, 0
	s_lshl_b32 s20, s79, 12
	s_sub_i32 s58, s58, s20
	s_sub_i32 s58, s58, s24
	s_add_i32 s58, s58, 0x2000000
	s_lshl_b32 s79, s79, 10
	s_add_u32 s24, s24, s16
	s_addc_u32 s25, s25, s17
	s_add_u32 s24, s24, 0x15c20000
	s_addc_u32 s25, s25, 0
	v_lshrrev_b32_e32 v217, 6, v214
	v_lshlrev_b32_e32 v217, 13, v217
	v_bfe_u32 v218, v214, 2, 3
	v_lshl_add_u32 v217, v218, 10, v217
	v_bfe_u32 v218, v214, 5, 1
	v_lshl_add_u32 v217, v218, 6, v217
	v_and_b32_e32 v218, 3, v214
	v_lshl_add_u32 v217, v218, 4, v217
	v_add_u32_e32 v233, s58, v217
	v_add_u32_e32 v234, 0x80, v233
	v_lshrrev_b32_e32 v217, 3, v214
	v_lshlrev_b32_e32 v217, 10, v217
	v_bfe_u32 v218, v214, 4, 3
	v_and_b32_e32 v232, 7, v214
	v_xor_b32_e32 v232, v232, v218
	v_lshl_add_u32 v232, v232, 4, v217
	v_add_u32_e32 v217, 0x10000, v232
	v_add_u32_e32 v232, 0x20000, v232
	s_waitcnt vmcnt(0)
	v_add_u32_e32 v218, 0x4000, v170
	ds_write_b128 v218, v[136:139] offset:49152
	s_add_i32 m0, s79, 0x12000
	s_nop 0
	global_load_lds_dwordx4 v217, s[24:25]
	v_readfirstlane_b32 s58, v214
	s_setprio 0
	s_lshr_b32 s58, s58, 8
	s_cmp_lg_u32 s58, 1
	s_cbranch_scc1 .Lat_noprio
	s_setprio 1
; #define SBAR() __builtin_amdgcn_sched_barrier(0)
; #define SLOAD(i, k0) do { sr_[i].vs0 = *reinterpret_cast<const bf16x8*>(&Vh[(long)((k0) + sr) * LDQ + sc]); sr_[i].vs1 = *reinterpret_cast<const bf16x8*>(&Vh[(long)((k0) + 32 + sr) * LDQ + sc]); \
;     sr_[i].ks0 = *reinterpret_cast<const bf16x8*>(&Kh[(long)((k0) + kr) * LDQ + kc]); } while (0)
; #define SWRITE(b, i) do { *(bf16x8*)(V_lds + (b) * SHM_V + vst0) = sr_[i].vs0; *(bf16x8*)(V_lds + (b) * SHM_V + vst1) = sr_[i].vs1; \
;     *(bf16x8*)(K_lds + (b) * SHM_K + kst) = sr_[i].ks0; } while (0)
; #define SWAIT() asm volatile("s_waitcnt vmcnt(3)" ::: "memory")
; #define RESC(a) do { if (__any((a) < 1.f)) { if (hi == 0) al_l[r32] = (a); asm volatile("s_waitcnt lgkmcnt(0)" ::: "memory"); \
;     _Pragma("unroll") for (int d = 0; d < 4; ++d) _Pragma("unroll") for (int r = 0; r < 16; ++r) o[d][r] *= al_l[crow(r, hi)]; } } while (0)
; #define ROT3() do { const int t_ = bp; bp = bc; bc = bn; bn = t_; } while (0)
; __device__ __forceinline__ void qkt(f32x16& p0, f32x16& p1, const char* Ks, const bf16x8* qr, int r32, int hi, float m_ref) {
; #pragma unroll
;   for (int r = 0; r < 16; ++r) { p0[r] = -m_ref; p1[r] = -m_ref; }
; #pragma unroll
;   for (int d0 = 0; d0 < 4; ++d0) { const int cb = (d0 * 16 + hi * 8) * 2;
;     bf16x8 b0 = *reinterpret_cast<const bf16x8*>(Ks + KSWZ(r32, cb));
;     bf16x8 b1 = *reinterpret_cast<const bf16x8*>(Ks + KSWZ(32 + r32, cb));
;     p0 = __builtin_amdgcn_mfma_f32_32x32x16_bf16(b0, qr[d0], p0, 0, 0, 0);
;     p1 = __builtin_amdgcn_mfma_f32_32x32x16_bf16(b1, qr[d0], p1, 0, 0, 0); }
; }
; __device__ __forceinline__ void attn_unit(const bf16_t* __restrict__ Qb, const bf16_t* __restrict__ Kh, const bf16_t* __restrict__ Vh, int seq, char* lds,
;                                           int mode, float* scratch, float lam, float gscale, const float* __restrict__ subg, bf16_t* outp) {
;     ...
;   for (int j = 1; j + 1 < NT; j += 2) {
;     SBAR(); qkt(pB0, pB1, K_lds + bc * SHM_K, qr, r32, hi, m_reg);
;     finishSM(pA0, pA1, alA, l_reg, pa0, pa1, pa2, pa3); SBAR();
;     SLOAD(SO, (j + 2) * KVBLK); SBAR();
;     pv_d0(o, vb0 + bp * SHM_V, pa0, pa1, pa2, pa3); partialSM(pB0, pB1, m_reg, alB, false);
;     SWAIT(); SWRITE(bn, SE);
;     RESC(alB); __syncthreads(); ROT3();
.Lat_noprio:
	s_waitcnt lgkmcnt(0)
	v_xor_b32_e32 v128, 0x80000000, v181
	v_mov_b32_e32 v129, v128
	v_mov_b32_e32 v130, v128
	v_mov_b32_e32 v131, v128
	v_mov_b32_e32 v132, v128
	v_mov_b32_e32 v133, v128
	v_mov_b32_e32 v134, v128
	v_mov_b32_e32 v135, v128
	v_mov_b32_e32 v136, v128
	v_mov_b32_e32 v137, v128
	v_mov_b32_e32 v138, v128
	v_mov_b32_e32 v139, v128
	v_mov_b32_e32 v140, v128
	v_mov_b32_e32 v141, v128
	v_mov_b32_e32 v142, v128
	v_mov_b32_e32 v143, v128
	s_barrier
	s_mov_b32 s58, 0x2000
	v_add_u32_e32 v218, s58, v173
	ds_read_b128 v[182:185], v218 offset:49152
	ds_read_b128 v[186:189], v218 offset:53248
	v_add_u32_e32 v218, s58, v175
	ds_read_b128 v[190:193], v218 offset:49152
	ds_read_b128 v[194:197], v218 offset:53248
	v_add_u32_e32 v218, s58, v174
	ds_read_b128 v[198:201], v218 offset:49152
	ds_read_b128 v[202:205], v218 offset:53248
	v_add_u32_e32 v218, s58, v176
	ds_read_b128 v[206:209], v218 offset:49152
	ds_read_b128 v[210:213], v218 offset:53248
.Lat_loop:
	s_mov_b32 s21, 0
	s_lshl_b32 s20, s0, 14
	s_add_i32 s20, s20, s79
	s_add_i32 m0, s20, s79
	s_add_i32 s20, s52, 3
	global_load_lds_dwordx4 v233, s[24:25]
	s_add_i32 m0, m0, 0x400
	s_and_b32 s20, s20, 3
	global_load_lds_dwordx4 v234, s[24:25]
	s_lshl_b32 s20, s20, 13
	s_add_i32 s20, s20, s79
	s_add_i32 m0, s20, 0xc000
	s_nop 0
	global_load_lds_dwordx4 v232, s[24:25]
	s_add_u32 s24, s24, 0x10000
	s_addc_u32 s25, s25, 0
	v_add_f32_e32 v159, v64, v65
	v_cvt_pk_bf16_f32 v64, v64, v65
	v_add_f32_e32 v160, v66, v67
	v_cvt_pk_bf16_f32 v65, v66, v67
	v_add_f32_e32 v159, v68, v159
	s_waitcnt lgkmcnt(7)
	v_mfma_f32_32x32x16_bf16 v[96:111], v[182:185], v[124:127], v[128:143]
	v_add_f32_e32 v160, v69, v160
	v_cvt_pk_bf16_f32 v66, v68, v69
	v_add_f32_e32 v159, v70, v159
	v_add_f32_e32 v160, v71, v160
	v_cvt_pk_bf16_f32 v67, v70, v71
	v_add_f32_e32 v159, v72, v159
	s_waitcnt lgkmcnt(6)
	v_mfma_f32_32x32x16_bf16 v[236:251], v[186:189], v[124:127], v[128:143]
	v_add_f32_e32 v160, v73, v160
	v_cvt_pk_bf16_f32 v68, v72, v73
	v_add_f32_e32 v159, v74, v159
	v_add_f32_e32 v160, v75, v160
	v_cvt_pk_bf16_f32 v69, v74, v75
	s_waitcnt lgkmcnt(5)
	v_mfma_f32_32x32x16_bf16 v[96:111], v[190:193], v[120:123], v[96:111]
	v_add_f32_e32 v159, v76, v159
	v_add_f32_e32 v160, v77, v160
	v_cvt_pk_bf16_f32 v70, v76, v77
	v_add_f32_e32 v159, v78, v159
	v_add_f32_e32 v160, v79, v160
	v_cvt_pk_bf16_f32 v71, v78, v79
	s_waitcnt lgkmcnt(4)
	v_mfma_f32_32x32x16_bf16 v[236:251], v[194:197], v[120:123], v[236:251]
	s_lshl_b32 s59, s2, 14
	v_add_u32_e32 v172, s59, v177
	ds_read_b64_tr_b16 v[182:183], v172 offset:0x0
	ds_read_b64_tr_b16 v[184:185], v172 offset:0x800
	ds_read_b64_tr_b16 v[186:187], v172 offset:0x1000
	ds_read_b64_tr_b16 v[188:189], v172 offset:0x1800
	ds_read_b64_tr_b16 v[190:191], v172 offset:0x2000
	ds_read_b64_tr_b16 v[192:193], v172 offset:0x2800
	ds_read_b64_tr_b16 v[194:195], v172 offset:0x3000
	ds_read_b64_tr_b16 v[196:197], v172 offset:0x3800
	v_add_f32_e32 v159, v80, v159
	v_add_f32_e32 v160, v81, v160
	v_cvt_pk_bf16_f32 v72, v80, v81
	v_add_f32_e32 v159, v82, v159
	v_add_f32_e32 v160, v83, v160
	v_cvt_pk_bf16_f32 v73, v82, v83
	s_waitcnt lgkmcnt(11)
	v_mfma_f32_32x32x16_bf16 v[96:111], v[198:201], v[116:119], v[96:111]
	v_add_f32_e32 v159, v84, v159
	v_add_f32_e32 v160, v85, v160
	v_cvt_pk_bf16_f32 v74, v84, v85
	v_add_f32_e32 v159, v86, v159
	v_add_f32_e32 v160, v87, v160
	v_cvt_pk_bf16_f32 v75, v86, v87
	s_waitcnt lgkmcnt(10)
	v_mfma_f32_32x32x16_bf16 v[236:251], v[202:205], v[116:119], v[236:251]
	s_waitcnt lgkmcnt(8)
	ds_read_b64_tr_b16 v[198:199], v172 offset:0x200
	ds_read_b64_tr_b16 v[200:201], v172 offset:0xa00
	ds_read_b64_tr_b16 v[202:203], v172 offset:0x1200
	ds_read_b64_tr_b16 v[204:205], v172 offset:0x1a00
	v_add_f32_e32 v159, v88, v159
	v_add_f32_e32 v160, v89, v160
	v_cvt_pk_bf16_f32 v76, v88, v89
	v_add_f32_e32 v159, v90, v159
	v_add_f32_e32 v160, v91, v160
	v_cvt_pk_bf16_f32 v77, v90, v91
	v_add_f32_e32 v159, v92, v159
	v_mfma_f32_32x32x16_bf16 v[96:111], v[206:209], v[112:115], v[96:111]
	ds_read_b64_tr_b16 v[206:207], v172 offset:0x2200
	ds_read_b64_tr_b16 v[208:209], v172 offset:0x2a00
	v_add_f32_e32 v160, v93, v160
	v_cvt_pk_bf16_f32 v78, v92, v93
	v_add_f32_e32 v159, v94, v159
	v_add_f32_e32 v160, v95, v160
	v_cvt_pk_bf16_f32 v79, v94, v95
	v_add_f32_e32 v159, v159, v160
	v_fma_f32 v167, v167, v235, v159
	v_mfma_f32_32x32x16_bf16 v[236:251], v[210:213], v[112:115], v[236:251]
	s_waitcnt lgkmcnt(12)
	v_mfma_f32_32x32x16_bf16 v[0:15], v[64:67], v[182:185], v[0:15]
	ds_read_b64_tr_b16 v[210:211], v172 offset:0x3200
	ds_read_b64_tr_b16 v[212:213], v172 offset:0x3a00
	v_max3_f32 v161, v96, v97, v98
	v_max3_f32 v161, v161, v99, v100
	v_max3_f32 v161, v161, v101, v102
	v_max3_f32 v161, v161, v103, v104
	s_waitcnt lgkmcnt(12)
	v_mfma_f32_32x32x16_bf16 v[0:15], v[68:71], v[186:189], v[0:15]
	ds_read_b64_tr_b16 v[182:183], v172 offset:0x400
	ds_read_b64_tr_b16 v[184:185], v172 offset:0xc00
	v_max3_f32 v161, v161, v105, v106
	v_max3_f32 v161, v161, v107, v108
	v_max3_f32 v161, v161, v109, v110
	v_max_f32_e32 v161, v161, v111
	s_waitcnt lgkmcnt(12)
	v_mfma_f32_32x32x16_bf16 v[0:15], v[72:75], v[190:193], v[0:15]
	ds_read_b64_tr_b16 v[186:187], v172 offset:0x1400
	ds_read_b64_tr_b16 v[188:189], v172 offset:0x1c00
	v_max3_f32 v216, v236, v237, v238
	v_max3_f32 v216, v216, v239, v240
	v_max3_f32 v216, v216, v241, v242
	v_max3_f32 v216, v216, v243, v244
	s_waitcnt lgkmcnt(12)
	v_mfma_f32_32x32x16_bf16 v[0:15], v[76:79], v[194:197], v[0:15]
	ds_read_b64_tr_b16 v[190:191], v172 offset:0x2400
	ds_read_b64_tr_b16 v[192:193], v172 offset:0x2c00
	v_max3_f32 v216, v216, v245, v246
	v_max3_f32 v216, v216, v247, v248
	v_max3_f32 v216, v216, v249, v250
	v_max_f32_e32 v216, v216, v251
	v_max_f32_e32 v161, v161, v216
	v_cmp_ge_f32_e32 vcc, s66, v161
	s_cmp_eq_u64 vcc, exec
	s_cbranch_scc0 .Lat_rare0
	v_mov_b32_e32 v158, 1.0
; #define SBAR() __builtin_amdgcn_sched_barrier(0)
; #define SLOAD(i, k0) do { sr_[i].vs0 = *reinterpret_cast<const bf16x8*>(&Vh[(long)((k0) + sr) * LDQ + sc]); sr_[i].vs1 = *reinterpret_cast<const bf16x8*>(&Vh[(long)((k0) + 32 + sr) * LDQ + sc]); \
;     sr_[i].ks0 = *reinterpret_cast<const bf16x8*>(&Kh[(long)((k0) + kr) * LDQ + kc]); } while (0)
; #define SWRITE(b, i) do { *(bf16x8*)(V_lds + (b) * SHM_V + vst0) = sr_[i].vs0; *(bf16x8*)(V_lds + (b) * SHM_V + vst1) = sr_[i].vs1; \
;     *(bf16x8*)(K_lds + (b) * SHM_K + kst) = sr_[i].ks0; } while (0)
; #define SWAIT() asm volatile("s_waitcnt vmcnt(3)" ::: "memory")
; #define ROT3() do { const int t_ = bp; bp = bc; bc = bn; bn = t_; } while (0)
; template <int D0> __device__ __forceinline__ void pv_one(f32x16& od, int vb, bf16x8 pa0, bf16x8 pa1, bf16x8 pa2, bf16x8 pa3) {
;   const s16x4 l0 = tr_read<v_rd_off(D0, 0, 0)>(vb), h0 = tr_read<v_rd_off(D0, 0, 1)>(vb), l1 = tr_read<v_rd_off(D0, 1, 0)>(vb), h1 = tr_read<v_rd_off(D0, 1, 1)>(vb);
;   const s16x4 l2 = tr_read<v_rd_off(D0, 2, 0)>(vb), h2 = tr_read<v_rd_off(D0, 2, 1)>(vb), l3 = tr_read<v_rd_off(D0, 3, 0)>(vb), h3 = tr_read<v_rd_off(D0, 3, 1)>(vb);
;   asm volatile("s_waitcnt lgkmcnt(0)" ::: "memory"); SBAR();
;     ...
;   od = __builtin_amdgcn_mfma_f32_32x32x16_bf16(pa0, PK(l0, h0), od, 0, 0, 0);
;   od = __builtin_amdgcn_mfma_f32_32x32x16_bf16(pa1, PK(l1, h1), od, 0, 0, 0);
;   od = __builtin_amdgcn_mfma_f32_32x32x16_bf16(pa2, PK(l2, h2), od, 0, 0, 0);
;   od = __builtin_amdgcn_mfma_f32_32x32x16_bf16(pa3, PK(l3, h3), od, 0, 0, 0);
; __device__ __forceinline__ void attn_unit(const bf16_t* __restrict__ Qb, const bf16_t* __restrict__ Kh, const bf16_t* __restrict__ Vh, int seq, char* lds,
;                                           int mode, float* scratch, float lam, float gscale, const float* __restrict__ subg, bf16_t* outp) {
;     ...
;     pv_d0(o, vb0 + bp * SHM_V, pa0, pa1, pa2, pa3); partialSM(pB0, pB1, m_reg, alB, false);
;     SWAIT(); SWRITE(bn, SE);
;     RESC(alB); __syncthreads(); ROT3();
;     SBAR(); qkt(pA0, pA1, K_lds + bc * SHM_K, qr, r32, hi, m_reg);
;     finishSM(pB0, pB1, alB, l_reg, pa0, pa1, pa2, pa3); SBAR();
;     if (j + 3 < NT) SLOAD(SE, (j + 3) * KVBLK); SBAR();
;     pv_d0(o, vb0 + bp * SHM_V, pa0, pa1, pa2, pa3); partialSM(pA0, pA1, m_reg, alA, false);
;     SWAIT(); SWRITE(bn, SO);
.Lat_back0:
	s_waitcnt lgkmcnt(12)
	v_mfma_f32_32x32x16_bf16 v[48:63], v[64:67], v[198:201], v[48:63]
	ds_read_b64_tr_b16 v[194:195], v172 offset:0x3400
	ds_read_b64_tr_b16 v[196:197], v172 offset:0x3c00
	v_exp_f32_e32 v96, v96
	v_exp_f32_e32 v97, v97
	v_exp_f32_e32 v98, v98
	s_waitcnt lgkmcnt(12)
	v_mfma_f32_32x32x16_bf16 v[48:63], v[68:71], v[202:205], v[48:63]
	ds_read_b64_tr_b16 v[198:199], v172 offset:0x600
	ds_read_b64_tr_b16 v[200:201], v172 offset:0xe00
	v_exp_f32_e32 v99, v99
	v_exp_f32_e32 v100, v100
	v_exp_f32_e32 v101, v101
	s_waitcnt lgkmcnt(12)
	v_mfma_f32_32x32x16_bf16 v[48:63], v[72:75], v[206:209], v[48:63]
	ds_read_b64_tr_b16 v[202:203], v172 offset:0x1600
	ds_read_b64_tr_b16 v[204:205], v172 offset:0x1e00
	v_exp_f32_e32 v102, v102
	v_exp_f32_e32 v103, v103
	v_exp_f32_e32 v104, v104
	s_waitcnt lgkmcnt(12)
	v_mfma_f32_32x32x16_bf16 v[48:63], v[76:79], v[210:213], v[48:63]
	ds_read_b64_tr_b16 v[206:207], v172 offset:0x2600
	ds_read_b64_tr_b16 v[208:209], v172 offset:0x2e00
	v_exp_f32_e32 v105, v105
	v_exp_f32_e32 v106, v106
	v_exp_f32_e32 v107, v107
	s_waitcnt lgkmcnt(12)
	v_mfma_f32_32x32x16_bf16 v[32:47], v[64:67], v[182:185], v[32:47]
	ds_read_b64_tr_b16 v[210:211], v172 offset:0x3600
	ds_read_b64_tr_b16 v[212:213], v172 offset:0x3e00
	s_add_i32 s58, s52, 1
	s_and_b32 s58, s58, 3
	s_lshl_b32 s58, s58, 13
	v_add_u32_e32 v218, s58, v173
	ds_read_b128 v[182:185], v218 offset:49152
	v_exp_f32_e32 v108, v108
	v_exp_f32_e32 v109, v109
	v_exp_f32_e32 v110, v110
	s_waitcnt lgkmcnt(13)
	v_mfma_f32_32x32x16_bf16 v[32:47], v[68:71], v[186:189], v[32:47]
	ds_read_b128 v[186:189], v218 offset:53248
	v_exp_f32_e32 v111, v111
	v_exp_f32_e32 v236, v236
	v_exp_f32_e32 v237, v237
	s_waitcnt lgkmcnt(12)
	v_mfma_f32_32x32x16_bf16 v[32:47], v[72:75], v[190:193], v[32:47]
	v_add_u32_e32 v218, s58, v175
	ds_read_b128 v[190:193], v218 offset:49152
	v_exp_f32_e32 v238, v238
	v_exp_f32_e32 v239, v239
	v_exp_f32_e32 v240, v240
	s_waitcnt lgkmcnt(11)
	v_mfma_f32_32x32x16_bf16 v[32:47], v[76:79], v[194:197], v[32:47]
	ds_read_b128 v[194:197], v218 offset:53248
	v_exp_f32_e32 v241, v241
	v_exp_f32_e32 v242, v242
	v_exp_f32_e32 v243, v243
	s_waitcnt lgkmcnt(10)
	v_mfma_f32_32x32x16_bf16 v[16:31], v[64:67], v[198:201], v[16:31]
	v_add_u32_e32 v218, s58, v174
	ds_read_b128 v[198:201], v218 offset:49152
	v_exp_f32_e32 v244, v244
	v_exp_f32_e32 v245, v245
	s_waitcnt lgkmcnt(9)
	v_mfma_f32_32x32x16_bf16 v[16:31], v[68:71], v[202:205], v[16:31]
	ds_read_b128 v[202:205], v218 offset:53248
	v_exp_f32_e32 v246, v246
	v_exp_f32_e32 v247, v247
	s_waitcnt lgkmcnt(8)
	v_mfma_f32_32x32x16_bf16 v[16:31], v[72:75], v[206:209], v[16:31]
	v_add_u32_e32 v218, s58, v176
	ds_read_b128 v[206:209], v218 offset:49152
	v_exp_f32_e32 v248, v248
	v_exp_f32_e32 v249, v249
	s_waitcnt lgkmcnt(7)
	v_mfma_f32_32x32x16_bf16 v[16:31], v[76:79], v[210:213], v[16:31]
	ds_read_b128 v[210:213], v218 offset:53248
	v_exp_f32_e32 v250, v250
	v_exp_f32_e32 v251, v251
	s_cmp_lg_u32 s21, 0
	s_cbranch_scc1 .Lat_resc0
.Lat_rescback0:
	s_waitcnt vmcnt(3)
	s_barrier
	s_mov_b32 s21, 0
	s_lshl_b32 s20, s2, 14
	s_add_i32 s20, s20, s79
	s_add_i32 m0, s20, s79
	s_add_i32 s20, s52, 4
	global_load_lds_dwordx4 v233, s[24:25]
	s_add_i32 m0, m0, 0x400
	s_and_b32 s20, s20, 3
	global_load_lds_dwordx4 v234, s[24:25]
	s_lshl_b32 s20, s20, 13
	s_add_i32 s20, s20, s79
	s_add_i32 m0, s20, 0xc000
	s_nop 0
	global_load_lds_dwordx4 v232, s[24:25]
	s_add_u32 s24, s24, 0x10000
	s_addc_u32 s25, s25, 0
	v_add_f32_e32 v159, v96, v97
	v_cvt_pk_bf16_f32 v96, v96, v97
	v_add_f32_e32 v160, v98, v99
	v_cvt_pk_bf16_f32 v97, v98, v99
	v_add_f32_e32 v159, v100, v159
	s_waitcnt lgkmcnt(7)
	v_mfma_f32_32x32x16_bf16 v[64:79], v[182:185], v[124:127], v[128:143]
	v_add_f32_e32 v160, v101, v160
	v_cvt_pk_bf16_f32 v98, v100, v101
	v_add_f32_e32 v159, v102, v159
	v_add_f32_e32 v160, v103, v160
	v_cvt_pk_bf16_f32 v99, v102, v103
	v_add_f32_e32 v159, v104, v159
	s_waitcnt lgkmcnt(6)
	v_mfma_f32_32x32x16_bf16 v[80:95], v[186:189], v[124:127], v[128:143]
	v_add_f32_e32 v160, v105, v160
	v_cvt_pk_bf16_f32 v100, v104, v105
	v_add_f32_e32 v159, v106, v159
	v_add_f32_e32 v160, v107, v160
	v_cvt_pk_bf16_f32 v101, v106, v107
	s_waitcnt lgkmcnt(5)
	v_mfma_f32_32x32x16_bf16 v[64:79], v[190:193], v[120:123], v[64:79]
	v_add_f32_e32 v159, v108, v159
	v_add_f32_e32 v160, v109, v160
	v_cvt_pk_bf16_f32 v102, v108, v109
	v_add_f32_e32 v159, v110, v159
	v_add_f32_e32 v160, v111, v160
	v_cvt_pk_bf16_f32 v103, v110, v111
	s_waitcnt lgkmcnt(4)
	v_mfma_f32_32x32x16_bf16 v[80:95], v[194:197], v[120:123], v[80:95]
	s_lshl_b32 s59, s1, 14
	v_add_u32_e32 v172, s59, v177
	ds_read_b64_tr_b16 v[182:183], v172 offset:0x0
	ds_read_b64_tr_b16 v[184:185], v172 offset:0x800
	ds_read_b64_tr_b16 v[186:187], v172 offset:0x1000
	ds_read_b64_tr_b16 v[188:189], v172 offset:0x1800
	ds_read_b64_tr_b16 v[190:191], v172 offset:0x2000
	ds_read_b64_tr_b16 v[192:193], v172 offset:0x2800
	ds_read_b64_tr_b16 v[194:195], v172 offset:0x3000
	ds_read_b64_tr_b16 v[196:197], v172 offset:0x3800
	v_add_f32_e32 v159, v236, v159
	v_add_f32_e32 v160, v237, v160
	v_cvt_pk_bf16_f32 v104, v236, v237
	v_add_f32_e32 v159, v238, v159
	v_add_f32_e32 v160, v239, v160
	v_cvt_pk_bf16_f32 v105, v238, v239
	s_waitcnt lgkmcnt(11)
	v_mfma_f32_32x32x16_bf16 v[64:79], v[198:201], v[116:119], v[64:79]
	v_add_f32_e32 v159, v240, v159
	v_add_f32_e32 v160, v241, v160
	v_cvt_pk_bf16_f32 v106, v240, v241
	v_add_f32_e32 v159, v242, v159
	v_add_f32_e32 v160, v243, v160
	v_cvt_pk_bf16_f32 v107, v242, v243
	s_waitcnt lgkmcnt(10)
	v_mfma_f32_32x32x16_bf16 v[80:95], v[202:205], v[116:119], v[80:95]
	s_waitcnt lgkmcnt(8)
; __device__ __forceinline__ void partialSM(f32x16& p0, f32x16& p1, float& m_ref, float& alpha, bool first) {
;   constexpr float THRL = THR * 1.4426950408889634f;
;   float pmax = p0[0];
; #pragma unroll
;   for (int r = 1; r < 16; ++r) pmax = fmaxf(pmax, p0[r]);
; #pragma unroll
;   for (int r = 0; r < 16; ++r) pmax = fmaxf(pmax, p1[r]);
;   { auto rr = __builtin_amdgcn_permlane32_swap(__float_as_uint(pmax), __float_as_uint(pmax), false, false);
;     pmax = fmaxf(__uint_as_float(rr[0]), __uint_as_float(rr[1])); }
;   if (__builtin_expect(!first && __all(pmax <= THRL), 1)) { alpha = 1.f; }
;   else { const float dl = first ? pmax : fmaxf(pmax, 0.f); m_ref += dl; alpha = first ? 1.f : __builtin_amdgcn_exp2f(-dl);
; #pragma unroll
;     for (int r = 0; r < 16; ++r) { p0[r] -= dl; p1[r] -= dl; } }
; #pragma unroll
;   for (int r = 0; r < 16; ++r) p0[r] = __builtin_amdgcn_exp2f(p0[r]);
; }
; __device__ __forceinline__ void finishSM(f32x16& p0, f32x16& p1, float alpha, float& l_reg, bf16x8& pa0, bf16x8& pa1, bf16x8& pa2, bf16x8& pa3) {
; #pragma unroll
;   for (int r = 0; r < 16; ++r) p1[r] = __builtin_amdgcn_exp2f(p1[r]);
;   float ps = 0;
; #pragma unroll
;   for (int r = 0; r < 16; ++r) ps += p0[r];
; #pragma unroll
;   for (int r = 0; r < 16; ++r) ps += p1[r];
;   { auto rr = __builtin_amdgcn_permlane32_swap(__float_as_uint(ps), __float_as_uint(ps), false, false);
;     ps = __uint_as_float(rr[0]) + __uint_as_float(rr[1]); }
;   l_reg = l_reg * alpha + ps;
;     ...
;   PK4(p0, 0, pa0); PK4(p0, 8, pa1); PK4(p1, 0, pa2); PK4(p1, 8, pa3);
;     ...
; }
; __device__ __forceinline__ void attn_unit(const bf16_t* __restrict__ Qb, const bf16_t* __restrict__ Kh, const bf16_t* __restrict__ Vh, int seq, char* lds,
;                                           int mode, float* scratch, float lam, float gscale, const float* __restrict__ subg, bf16_t* outp) {
;     ...
;   for (int j = 1; j + 1 < NT; j += 2) {
;     SBAR(); qkt(pB0, pB1, K_lds + bc * SHM_K, qr, r32, hi, m_reg);
;     finishSM(pA0, pA1, alA, l_reg, pa0, pa1, pa2, pa3); SBAR();
;     SLOAD(SO, (j + 2) * KVBLK); SBAR();
;     pv_d0(o, vb0 + bp * SHM_V, pa0, pa1, pa2, pa3); partialSM(pB0, pB1, m_reg, alB, false);
;     SWAIT(); SWRITE(bn, SE);
;     RESC(alB); __syncthreads(); ROT3();
;     SBAR(); qkt(pA0, pA1, K_lds + bc * SHM_K, qr, r32, hi, m_reg);
;     finishSM(pB0, pB1, alB, l_reg, pa0, pa1, pa2, pa3); SBAR();
	ds_read_b64_tr_b16 v[198:199], v172 offset:0x200
	ds_read_b64_tr_b16 v[200:201], v172 offset:0xa00
	ds_read_b64_tr_b16 v[202:203], v172 offset:0x1200
	ds_read_b64_tr_b16 v[204:205], v172 offset:0x1a00
	v_add_f32_e32 v159, v244, v159
	v_add_f32_e32 v160, v245, v160
	v_cvt_pk_bf16_f32 v108, v244, v245
	v_add_f32_e32 v159, v246, v159
	v_add_f32_e32 v160, v247, v160
	v_cvt_pk_bf16_f32 v109, v246, v247
	v_add_f32_e32 v159, v248, v159
	v_mfma_f32_32x32x16_bf16 v[64:79], v[206:209], v[112:115], v[64:79]
	ds_read_b64_tr_b16 v[206:207], v172 offset:0x2200
	ds_read_b64_tr_b16 v[208:209], v172 offset:0x2a00
	v_add_f32_e32 v160, v249, v160
	v_cvt_pk_bf16_f32 v110, v248, v249
	v_add_f32_e32 v159, v250, v159
	v_add_f32_e32 v160, v251, v160
	v_cvt_pk_bf16_f32 v111, v250, v251
	v_add_f32_e32 v159, v159, v160
	v_fma_f32 v167, v167, v158, v159
	v_mfma_f32_32x32x16_bf16 v[80:95], v[210:213], v[112:115], v[80:95]
	s_waitcnt lgkmcnt(12)
	v_mfma_f32_32x32x16_bf16 v[0:15], v[96:99], v[182:185], v[0:15]
	ds_read_b64_tr_b16 v[210:211], v172 offset:0x3200
	ds_read_b64_tr_b16 v[212:213], v172 offset:0x3a00
	v_max3_f32 v161, v64, v65, v66
	v_max3_f32 v161, v161, v67, v68
	v_max3_f32 v161, v161, v69, v70
	v_max3_f32 v161, v161, v71, v72
	s_waitcnt lgkmcnt(12)
	v_mfma_f32_32x32x16_bf16 v[0:15], v[100:103], v[186:189], v[0:15]
	ds_read_b64_tr_b16 v[182:183], v172 offset:0x400
	ds_read_b64_tr_b16 v[184:185], v172 offset:0xc00
	v_max3_f32 v161, v161, v73, v74
	v_max3_f32 v161, v161, v75, v76
	v_max3_f32 v161, v161, v77, v78
	v_max_f32_e32 v161, v161, v79
	s_waitcnt lgkmcnt(12)
	v_mfma_f32_32x32x16_bf16 v[0:15], v[104:107], v[190:193], v[0:15]
	ds_read_b64_tr_b16 v[186:187], v172 offset:0x1400
	ds_read_b64_tr_b16 v[188:189], v172 offset:0x1c00
	v_max3_f32 v216, v80, v81, v82
	v_max3_f32 v216, v216, v83, v84
	v_max3_f32 v216, v216, v85, v86
	v_max3_f32 v216, v216, v87, v88
	s_waitcnt lgkmcnt(12)
	v_mfma_f32_32x32x16_bf16 v[0:15], v[108:111], v[194:197], v[0:15]
	ds_read_b64_tr_b16 v[190:191], v172 offset:0x2400
	ds_read_b64_tr_b16 v[192:193], v172 offset:0x2c00
	v_max3_f32 v216, v216, v89, v90
	v_max3_f32 v216, v216, v91, v92
	v_max3_f32 v216, v216, v93, v94
	v_max_f32_e32 v216, v216, v95
	v_max_f32_e32 v161, v161, v216
	v_cmp_ge_f32_e32 vcc, s66, v161
	s_cmp_eq_u64 vcc, exec
	s_cbranch_scc0 .Lat_rare1
	v_mov_b32_e32 v235, 1.0
.Lat_back1:
	s_waitcnt lgkmcnt(12)
	v_mfma_f32_32x32x16_bf16 v[48:63], v[96:99], v[198:201], v[48:63]
	ds_read_b64_tr_b16 v[194:195], v172 offset:0x3400
	ds_read_b64_tr_b16 v[196:197], v172 offset:0x3c00
	v_exp_f32_e32 v64, v64
	v_exp_f32_e32 v65, v65
	v_exp_f32_e32 v66, v66
	s_waitcnt lgkmcnt(12)
	v_mfma_f32_32x32x16_bf16 v[48:63], v[100:103], v[202:205], v[48:63]
	ds_read_b64_tr_b16 v[198:199], v172 offset:0x600
	ds_read_b64_tr_b16 v[200:201], v172 offset:0xe00
	v_exp_f32_e32 v67, v67
	v_exp_f32_e32 v68, v68
	v_exp_f32_e32 v69, v69
	s_waitcnt lgkmcnt(12)
	v_mfma_f32_32x32x16_bf16 v[48:63], v[104:107], v[206:209], v[48:63]
	ds_read_b64_tr_b16 v[202:203], v172 offset:0x1600
	ds_read_b64_tr_b16 v[204:205], v172 offset:0x1e00
	v_exp_f32_e32 v70, v70
	v_exp_f32_e32 v71, v71
	v_exp_f32_e32 v72, v72
	s_waitcnt lgkmcnt(12)
	v_mfma_f32_32x32x16_bf16 v[48:63], v[108:111], v[210:213], v[48:63]
	ds_read_b64_tr_b16 v[206:207], v172 offset:0x2600
	ds_read_b64_tr_b16 v[208:209], v172 offset:0x2e00
	v_exp_f32_e32 v73, v73
	v_exp_f32_e32 v74, v74
	v_exp_f32_e32 v75, v75
	s_waitcnt lgkmcnt(12)
	v_mfma_f32_32x32x16_bf16 v[32:47], v[96:99], v[182:185], v[32:47]
	ds_read_b64_tr_b16 v[210:211], v172 offset:0x3600
	ds_read_b64_tr_b16 v[212:213], v172 offset:0x3e00
	s_add_i32 s58, s52, 2
	s_and_b32 s58, s58, 3
	s_lshl_b32 s58, s58, 13
	v_add_u32_e32 v218, s58, v173
	ds_read_b128 v[182:185], v218 offset:49152
	v_exp_f32_e32 v76, v76
	v_exp_f32_e32 v77, v77
	v_exp_f32_e32 v78, v78
	s_waitcnt lgkmcnt(13)
	v_mfma_f32_32x32x16_bf16 v[32:47], v[100:103], v[186:189], v[32:47]
	ds_read_b128 v[186:189], v218 offset:53248
	v_exp_f32_e32 v79, v79
	v_exp_f32_e32 v80, v80
	v_exp_f32_e32 v81, v81
	s_waitcnt lgkmcnt(12)
	v_mfma_f32_32x32x16_bf16 v[32:47], v[104:107], v[190:193], v[32:47]
	v_add_u32_e32 v218, s58, v175
	ds_read_b128 v[190:193], v218 offset:49152
	v_exp_f32_e32 v82, v82
	v_exp_f32_e32 v83, v83
	v_exp_f32_e32 v84, v84
	s_waitcnt lgkmcnt(11)
	v_mfma_f32_32x32x16_bf16 v[32:47], v[108:111], v[194:197], v[32:47]
	ds_read_b128 v[194:197], v218 offset:53248
	v_exp_f32_e32 v85, v85
	v_exp_f32_e32 v86, v86
	v_exp_f32_e32 v87, v87
	s_waitcnt lgkmcnt(10)
	v_mfma_f32_32x32x16_bf16 v[16:31], v[96:99], v[198:201], v[16:31]
	v_add_u32_e32 v218, s58, v174
	ds_read_b128 v[198:201], v218 offset:49152
	v_exp_f32_e32 v88, v88
	v_exp_f32_e32 v89, v89
	s_waitcnt lgkmcnt(9)
	v_mfma_f32_32x32x16_bf16 v[16:31], v[100:103], v[202:205], v[16:31]
	ds_read_b128 v[202:205], v218 offset:53248
	v_exp_f32_e32 v90, v90
	v_exp_f32_e32 v91, v91
	s_waitcnt lgkmcnt(8)
	v_mfma_f32_32x32x16_bf16 v[16:31], v[104:107], v[206:209], v[16:31]
	v_add_u32_e32 v218, s58, v176
	ds_read_b128 v[206:209], v218 offset:49152
	v_exp_f32_e32 v92, v92
	v_exp_f32_e32 v93, v93
	s_waitcnt lgkmcnt(7)
	v_mfma_f32_32x32x16_bf16 v[16:31], v[108:111], v[210:213], v[16:31]
	ds_read_b128 v[210:213], v218 offset:53248
	v_exp_f32_e32 v94, v94
	v_exp_f32_e32 v95, v95
	s_cmp_lg_u32 s21, 0
	s_cbranch_scc1 .Lat_resc1
.Lat_rescback1:
	s_waitcnt vmcnt(3)
	s_add_i32 s52, s52, 2
	s_cmpk_gt_u32 s52, 0xfe
	s_barrier
	s_cbranch_scc1 .Lat_exit
	s_mov_b32 s58, s2
	s_mov_b32 s2, s0
	s_mov_b32 s0, s1
	s_mov_b32 s1, s58
	s_branch .Lat_loop
; __device__ __forceinline__ void partialSM(f32x16& p0, f32x16& p1, float& m_ref, float& alpha, bool first) {
;     ...
;   { auto rr = __builtin_amdgcn_permlane32_swap(__float_as_uint(pmax), __float_as_uint(pmax), false, false);
;     pmax = fmaxf(__uint_as_float(rr[0]), __uint_as_float(rr[1])); }
;   if (__builtin_expect(!first && __all(pmax <= THRL), 1)) { alpha = 1.f; }
;   else { const float dl = first ? pmax : fmaxf(pmax, 0.f); m_ref += dl; alpha = first ? 1.f : __builtin_amdgcn_exp2f(-dl);
; #pragma unroll
;     for (int r = 0; r < 16; ++r) { p0[r] -= dl; p1[r] -= dl; } }
; __device__ __forceinline__ void qkt(f32x16& p0, f32x16& p1, const char* Ks, const bf16x8* qr, int r32, int hi, float m_ref) {
;     ...
;   for (int r = 0; r < 16; ++r) { p0[r] = -m_ref; p1[r] = -m_ref; }
.Lat_rare0:
	v_mov_b32_e32 v216, v161
	s_mov_b32 s21, 1
	s_nop 1
	v_permlane32_swap_b32_e32 v161, v216
	v_max_f32_e32 v161, v161, v216
	v_max_f32_e32 v161, 0, v161
	v_exp_f32_e64 v158, -v161
	v_add_f32_e32 v181, v181, v161
	v_sub_f32_e32 v96, v96, v161
	v_sub_f32_e32 v97, v97, v161
	v_sub_f32_e32 v98, v98, v161
	v_sub_f32_e32 v99, v99, v161
	v_sub_f32_e32 v100, v100, v161
	v_sub_f32_e32 v101, v101, v161
	v_sub_f32_e32 v102, v102, v161
	v_sub_f32_e32 v103, v103, v161
	v_sub_f32_e32 v104, v104, v161
	v_sub_f32_e32 v105, v105, v161
	v_sub_f32_e32 v106, v106, v161
	v_sub_f32_e32 v107, v107, v161
	v_sub_f32_e32 v108, v108, v161
	v_sub_f32_e32 v109, v109, v161
	v_sub_f32_e32 v110, v110, v161
	v_sub_f32_e32 v111, v111, v161
	v_sub_f32_e32 v236, v236, v161
	v_sub_f32_e32 v237, v237, v161
	v_sub_f32_e32 v238, v238, v161
	v_sub_f32_e32 v239, v239, v161
	v_sub_f32_e32 v240, v240, v161
	v_sub_f32_e32 v241, v241, v161
	v_sub_f32_e32 v242, v242, v161
	v_sub_f32_e32 v243, v243, v161
	v_sub_f32_e32 v244, v244, v161
	v_sub_f32_e32 v245, v245, v161
	v_sub_f32_e32 v246, v246, v161
	v_sub_f32_e32 v247, v247, v161
	v_sub_f32_e32 v248, v248, v161
	v_sub_f32_e32 v249, v249, v161
	v_sub_f32_e32 v250, v250, v161
	v_sub_f32_e32 v251, v251, v161
	v_xor_b32_e32 v128, 0x80000000, v181
	v_mov_b32_e32 v129, v128
	v_mov_b32_e32 v130, v128
	v_mov_b32_e32 v131, v128
	v_mov_b32_e32 v132, v128
	v_mov_b32_e32 v133, v128
	v_mov_b32_e32 v134, v128
	v_mov_b32_e32 v135, v128
	v_mov_b32_e32 v136, v128
	v_mov_b32_e32 v137, v128
	v_mov_b32_e32 v138, v128
	v_mov_b32_e32 v139, v128
	v_mov_b32_e32 v140, v128
	v_mov_b32_e32 v141, v128
	v_mov_b32_e32 v142, v128
	v_mov_b32_e32 v143, v128
	s_branch .Lat_back0
.Lat_rare1:
	v_mov_b32_e32 v216, v161
	s_mov_b32 s21, 1
	s_nop 1
	v_permlane32_swap_b32_e32 v161, v216
	v_max_f32_e32 v161, v161, v216
	v_max_f32_e32 v161, 0, v161
	v_exp_f32_e64 v235, -v161
	v_add_f32_e32 v181, v181, v161
	v_sub_f32_e32 v64, v64, v161
	v_sub_f32_e32 v65, v65, v161
	v_sub_f32_e32 v66, v66, v161
	v_sub_f32_e32 v67, v67, v161
	v_sub_f32_e32 v68, v68, v161
	v_sub_f32_e32 v69, v69, v161
	v_sub_f32_e32 v70, v70, v161
	v_sub_f32_e32 v71, v71, v161
	v_sub_f32_e32 v72, v72, v161
	v_sub_f32_e32 v73, v73, v161
	v_sub_f32_e32 v74, v74, v161
	v_sub_f32_e32 v75, v75, v161
	v_sub_f32_e32 v76, v76, v161
	v_sub_f32_e32 v77, v77, v161
	v_sub_f32_e32 v78, v78, v161
	v_sub_f32_e32 v79, v79, v161
	v_sub_f32_e32 v80, v80, v161
	v_sub_f32_e32 v81, v81, v161
	v_sub_f32_e32 v82, v82, v161
	v_sub_f32_e32 v83, v83, v161
	v_sub_f32_e32 v84, v84, v161
	v_sub_f32_e32 v85, v85, v161
	v_sub_f32_e32 v86, v86, v161
	v_sub_f32_e32 v87, v87, v161
	v_sub_f32_e32 v88, v88, v161
	v_sub_f32_e32 v89, v89, v161
	v_sub_f32_e32 v90, v90, v161
	v_sub_f32_e32 v91, v91, v161
	v_sub_f32_e32 v92, v92, v161
	v_sub_f32_e32 v93, v93, v161
	v_sub_f32_e32 v94, v94, v161
	v_sub_f32_e32 v95, v95, v161
	v_xor_b32_e32 v128, 0x80000000, v181
	v_mov_b32_e32 v129, v128
	v_mov_b32_e32 v130, v128
	v_mov_b32_e32 v131, v128
	v_mov_b32_e32 v132, v128
	v_mov_b32_e32 v133, v128
	v_mov_b32_e32 v134, v128
	v_mov_b32_e32 v135, v128
	v_mov_b32_e32 v136, v128
	v_mov_b32_e32 v137, v128
	v_mov_b32_e32 v138, v128
	v_mov_b32_e32 v139, v128
	v_mov_b32_e32 v140, v128
	v_mov_b32_e32 v141, v128
	v_mov_b32_e32 v142, v128
	v_mov_b32_e32 v143, v128
	s_branch .Lat_back1
; #define SBAR() __builtin_amdgcn_sched_barrier(0)
; #define RESC(a) do { if (__any((a) < 1.f)) { if (hi == 0) al_l[r32] = (a); asm volatile("s_waitcnt lgkmcnt(0)" ::: "memory"); \
;     _Pragma("unroll") for (int d = 0; d < 4; ++d) _Pragma("unroll") for (int r = 0; r < 16; ++r) o[d][r] *= al_l[crow(r, hi)]; } } while (0)
; __device__ __forceinline__ void attn_unit(const bf16_t* __restrict__ Qb, const bf16_t* __restrict__ Kh, const bf16_t* __restrict__ Vh, int seq, char* lds,
;                                           int mode, float* scratch, float lam, float gscale, const float* __restrict__ subg, bf16_t* outp) {
;     ...
;   SBAR(); qkt(pB0, pB1, K_lds + bc * SHM_K, qr, r32, hi, m_reg);
;   finishSM(pA0, pA1, alA, l_reg, pa0, pa1, pa2, pa3); SBAR();
;   pv_d0(o, vb0 + bp * SHM_V, pa0, pa1, pa2, pa3); partialSM(pB0, pB1, m_reg, alB, false);
;   RESC(alB);
;   finishSM(pB0, pB1, alB, l_reg, pa0, pa1, pa2, pa3); SBAR();
;   pv_d0(o, vb0 + bc * SHM_V, pa0, pa1, pa2, pa3);
;   __builtin_amdgcn_s_setprio(0);
;     ...
;   if (hi == 0) li_l[r32] = l_reg; asm volatile("s_waitcnt lgkmcnt(0)" ::: "memory");
.Lat_resc0:
	s_and_saveexec_b64 s[58:59], s[4:5]
	ds_write_b32 v153, v158 offset:128
	s_or_b64 exec, exec, s[58:59]
	s_waitcnt lgkmcnt(0)
	v_add_u32_e32 v217, v166, v178
	ds_read_b128 v[144:147], v217 offset:224
	ds_read_b128 v[148:151], v217 offset:192
	s_waitcnt lgkmcnt(0)
	v_pk_mul_f32 v[12:13], v[12:13], v[144:145]
	v_pk_mul_f32 v[14:15], v[14:15], v[146:147]
	v_pk_mul_f32 v[8:9], v[8:9], v[148:149]
	v_pk_mul_f32 v[10:11], v[10:11], v[150:151]
	v_pk_mul_f32 v[60:61], v[60:61], v[144:145]
	v_pk_mul_f32 v[62:63], v[62:63], v[146:147]
	v_pk_mul_f32 v[56:57], v[56:57], v[148:149]
	v_pk_mul_f32 v[58:59], v[58:59], v[150:151]
	v_pk_mul_f32 v[44:45], v[44:45], v[144:145]
	v_pk_mul_f32 v[46:47], v[46:47], v[146:147]
	v_pk_mul_f32 v[40:41], v[40:41], v[148:149]
	v_pk_mul_f32 v[42:43], v[42:43], v[150:151]
	v_pk_mul_f32 v[28:29], v[28:29], v[144:145]
	v_pk_mul_f32 v[30:31], v[30:31], v[146:147]
	v_pk_mul_f32 v[24:25], v[24:25], v[148:149]
	v_pk_mul_f32 v[26:27], v[26:27], v[150:151]
	ds_read_b128 v[144:147], v217 offset:160
	ds_read_b128 v[148:151], v217 offset:128
	s_waitcnt lgkmcnt(0)
	v_pk_mul_f32 v[4:5], v[4:5], v[144:145]
	v_pk_mul_f32 v[6:7], v[6:7], v[146:147]
	v_pk_mul_f32 v[0:1], v[0:1], v[148:149]
	v_pk_mul_f32 v[2:3], v[2:3], v[150:151]
	v_pk_mul_f32 v[52:53], v[52:53], v[144:145]
	v_pk_mul_f32 v[54:55], v[54:55], v[146:147]
	v_pk_mul_f32 v[48:49], v[48:49], v[148:149]
	v_pk_mul_f32 v[50:51], v[50:51], v[150:151]
	v_pk_mul_f32 v[36:37], v[36:37], v[144:145]
	v_pk_mul_f32 v[38:39], v[38:39], v[146:147]
	v_pk_mul_f32 v[32:33], v[32:33], v[148:149]
	v_pk_mul_f32 v[34:35], v[34:35], v[150:151]
	v_pk_mul_f32 v[20:21], v[20:21], v[144:145]
	v_pk_mul_f32 v[22:23], v[22:23], v[146:147]
	v_pk_mul_f32 v[16:17], v[16:17], v[148:149]
	v_pk_mul_f32 v[18:19], v[18:19], v[150:151]
	s_branch .Lat_rescback0
.Lat_resc1:
	s_and_saveexec_b64 s[58:59], s[4:5]
	ds_write_b32 v153, v235 offset:128
	s_or_b64 exec, exec, s[58:59]
	s_waitcnt lgkmcnt(0)
	v_add_u32_e32 v217, v166, v178
	ds_read_b128 v[144:147], v217 offset:224
	ds_read_b128 v[148:151], v217 offset:192
	s_waitcnt lgkmcnt(0)
	v_pk_mul_f32 v[12:13], v[12:13], v[144:145]
	v_pk_mul_f32 v[14:15], v[14:15], v[146:147]
	v_pk_mul_f32 v[8:9], v[8:9], v[148:149]
	v_pk_mul_f32 v[10:11], v[10:11], v[150:151]
	v_pk_mul_f32 v[60:61], v[60:61], v[144:145]
	v_pk_mul_f32 v[62:63], v[62:63], v[146:147]
	v_pk_mul_f32 v[56:57], v[56:57], v[148:149]
	v_pk_mul_f32 v[58:59], v[58:59], v[150:151]
	v_pk_mul_f32 v[44:45], v[44:45], v[144:145]
	v_pk_mul_f32 v[46:47], v[46:47], v[146:147]
	v_pk_mul_f32 v[40:41], v[40:41], v[148:149]
	v_pk_mul_f32 v[42:43], v[42:43], v[150:151]
	v_pk_mul_f32 v[28:29], v[28:29], v[144:145]
	v_pk_mul_f32 v[30:31], v[30:31], v[146:147]
	v_pk_mul_f32 v[24:25], v[24:25], v[148:149]
	v_pk_mul_f32 v[26:27], v[26:27], v[150:151]
	ds_read_b128 v[144:147], v217 offset:160
	ds_read_b128 v[148:151], v217 offset:128
	s_waitcnt lgkmcnt(0)
	v_pk_mul_f32 v[4:5], v[4:5], v[144:145]
	v_pk_mul_f32 v[6:7], v[6:7], v[146:147]
	v_pk_mul_f32 v[0:1], v[0:1], v[148:149]
	v_pk_mul_f32 v[2:3], v[2:3], v[150:151]
	v_pk_mul_f32 v[52:53], v[52:53], v[144:145]
	v_pk_mul_f32 v[54:55], v[54:55], v[146:147]
	v_pk_mul_f32 v[48:49], v[48:49], v[148:149]
	v_pk_mul_f32 v[50:51], v[50:51], v[150:151]
	v_pk_mul_f32 v[36:37], v[36:37], v[144:145]
	v_pk_mul_f32 v[38:39], v[38:39], v[146:147]
	v_pk_mul_f32 v[32:33], v[32:33], v[148:149]
	v_pk_mul_f32 v[34:35], v[34:35], v[150:151]
	v_pk_mul_f32 v[20:21], v[20:21], v[144:145]
	v_pk_mul_f32 v[22:23], v[22:23], v[146:147]
	v_pk_mul_f32 v[16:17], v[16:17], v[148:149]
	v_pk_mul_f32 v[18:19], v[18:19], v[150:151]
	s_branch .Lat_rescback1
.Lat_exit:
	s_waitcnt vmcnt(0) lgkmcnt(0)
	s_barrier
	v_mov_b32_e32 v160, v64
	v_mov_b32_e32 v192, v65
	v_mov_b32_e32 v151, v66
	v_mov_b32_e32 v161, v67
	v_mov_b32_e32 v149, v68
	v_mov_b32_e32 v159, v69
	v_mov_b32_e32 v148, v70
	v_mov_b32_e32 v150, v71
	v_mov_b32_e32 v145, v72
	v_mov_b32_e32 v147, v73
	v_mov_b32_e32 v143, v74
	v_mov_b32_e32 v146, v75
	v_mov_b32_e32 v141, v76
	v_mov_b32_e32 v144, v77
	v_mov_b32_e32 v140, v78
	v_mov_b32_e32 v142, v79
	v_mov_b32_e32 v64, v80
	v_mov_b32_e32 v65, v81
	v_mov_b32_e32 v66, v82
	v_mov_b32_e32 v67, v83
	v_mov_b32_e32 v68, v84
	v_mov_b32_e32 v69, v85
	v_mov_b32_e32 v70, v86
	v_mov_b32_e32 v71, v87
	v_mov_b32_e32 v72, v88
	v_mov_b32_e32 v73, v89
	v_mov_b32_e32 v74, v90
	v_mov_b32_e32 v75, v91
	v_mov_b32_e32 v76, v92
	v_mov_b32_e32 v77, v93
	v_mov_b32_e32 v78, v94
	v_mov_b32_e32 v79, v95
	v_mov_b32_e32 v158, v235
	v_mov_b32_e32 v216, v167
	s_mov_b32 s1, s2
	s_lshl_b32 s59, s0, 14
	v_permlane32_swap_b32_e32 v167, v216
	v_add_f32_e32 v167, v167, v216
	s_lshl_b32 s2, s1, 14
	v_add_u32_e32 v172, s2, v177
	s_and_b32 s2, s52, 3
	s_lshl_b32 s2, s2, 13
	s_mov_b32 s79, 0
